# late prep-tile loop: hand-written lean next-tile raw-load issue (thread-constant decode, SGPR base + 32-bit offsets) replacing the branchy compiler version
# speedup vs baseline: 1.0089x; 1.0021x over previous
.LBB0_667:
	s_or_b64 exec, exec, s[26:27]
	v_and_b32_e32 v44, 63, v26
	v_readlane_b32 s2, v250, 60
	v_readlane_b32 s4, v251, 8
	v_readlane_b32 s10, v251, 14
	v_or_b32_e32 v2, s2, v44
	v_ashrrev_i32_e32 v3, 31, v2
	v_readlane_b32 s11, v251, 15
	s_waitcnt lgkmcnt(0)
	s_barrier
	v_lshl_add_u64 v[2:3], v[2:3], 2, s[10:11]
	global_load_dword v47, v[2:3], off
	v_ashrrev_i32_e32 v46, 5, v26
	v_and_b32_e32 v94, -2, v46
	s_movk_i32 s2, 0x1200
	v_lshlrev_b32_e32 v0, 2, v44
	v_mul_lo_u32 v4, v94, s2
	v_add3_u32 v48, 0, v4, v0
	ds_read_b32 v49, v48 offset:1536
	v_readlane_b32 s3, v250, 61
	v_readlane_b32 s2, v252, 20
	v_readlane_b32 s3, v252, 21
	s_ashr_i32 s35, s34, 31
	s_lshl_b64 s[34:35], s[34:35], 4
	v_lshl_add_u64 v[4:5], s[2:3], 0, v[0:1]
	v_ashrrev_i32_e32 v95, 31, v94
	v_lshl_add_u64 v[24:25], s[34:35], 0, v[94:95]
	v_lshlrev_b64 v[24:25], 10, v[24:25]
	v_cmp_eq_u32_e32 vcc, 0, v44
	v_lshl_add_u64 v[24:25], v[4:5], 0, v[24:25]
	v_readlane_b32 s5, v251, 9
	v_readlane_b32 s6, v251, 10
	v_readlane_b32 s7, v251, 11
	v_readlane_b32 s8, v251, 12
	v_readlane_b32 s9, v251, 13
	v_readlane_b32 s12, v251, 16
	v_readlane_b32 s13, v251, 17
	v_readlane_b32 s14, v251, 18
	v_readlane_b32 s15, v251, 19
	v_readlane_b32 s16, v251, 20
	v_readlane_b32 s17, v251, 21
	v_readlane_b32 s18, v251, 22
	v_readlane_b32 s19, v251, 23
	s_waitcnt vmcnt(0) lgkmcnt(0)
	v_mul_f32_e32 v52, v49, v47
	v_mul_f32_e32 v47, v52, v52
	s_nop 1
	v_mov_b32_dpp v47, v47 quad_perm:[1,0,3,2] row_mask:0xf bank_mask:0xf bound_ctrl:1
	v_fmac_f32_e32 v47, v52, v52
	s_nop 1
	v_add_f32_dpp v47, v47, v47 quad_perm:[2,3,0,1] row_mask:0xf bank_mask:0xf bound_ctrl:1
	s_nop 1
	v_add_f32_dpp v47, v47, v47 row_half_mirror row_mask:0xf bank_mask:0xf bound_ctrl:1
	s_nop 1
	v_add_f32_dpp v47, v47, v47 row_ror:8 row_mask:0xf bank_mask:0xf bound_ctrl:1
	s_nop 0
	v_readlane_b32 s2, v47, 16
	v_readlane_b32 s3, v47, 48
	v_readlane_b32 s26, v47, 0
	v_readlane_b32 s27, v47, 32
	v_mov_b32_e32 v50, s2
	v_mov_b32_e32 v51, s3
	v_pk_add_f32 v[50:51], s[26:27], v[50:51]
	s_nop 0
	v_add_f32_e32 v47, v50, v51
	v_rsq_f32_e32 v49, v47
	v_lshlrev_b32_e32 v47, 4, v94
	v_min_f32_e32 v49, 0x5368d4a5, v49
	v_mul_f32_e32 v50, v52, v49
	global_store_dword v[24:25], v50, off
	s_and_saveexec_b64 s[26:27], vcc
	v_add_u32_e32 v50, 0, v47
	v_add_u32_e32 v50, 0x12000, v50
	ds_write_b32 v50, v49
	s_or_b64 exec, exec, s[26:27]
	global_load_dword v49, v[2:3], off offset:256
	ds_read_b32 v50, v48 offset:1792
	s_waitcnt vmcnt(0) lgkmcnt(0)
	v_mul_f32_e32 v52, v50, v49
	v_mul_f32_e32 v49, v52, v52
	s_nop 1
	v_mov_b32_dpp v49, v49 quad_perm:[1,0,3,2] row_mask:0xf bank_mask:0xf bound_ctrl:1
	v_fmac_f32_e32 v49, v52, v52
	s_nop 1
	v_add_f32_dpp v49, v49, v49 quad_perm:[2,3,0,1] row_mask:0xf bank_mask:0xf bound_ctrl:1
	s_nop 1
	v_add_f32_dpp v49, v49, v49 row_half_mirror row_mask:0xf bank_mask:0xf bound_ctrl:1
	s_nop 1
	v_add_f32_dpp v49, v49, v49 row_ror:8 row_mask:0xf bank_mask:0xf bound_ctrl:1
	s_nop 0
	v_readlane_b32 s2, v49, 16
	v_readlane_b32 s3, v49, 48
	v_readlane_b32 s26, v49, 0
	v_readlane_b32 s27, v49, 32
	v_mov_b32_e32 v50, s2
	v_mov_b32_e32 v51, s3
	v_pk_add_f32 v[50:51], s[26:27], v[50:51]
	s_nop 0
	v_add_f32_e32 v49, v50, v51
	v_rsq_f32_e32 v49, v49
	s_nop 0
	v_min_f32_e32 v49, 0x5368d4a5, v49
	v_mul_f32_e32 v50, v52, v49
	global_store_dword v[24:25], v50, off offset:256
	s_and_saveexec_b64 s[26:27], vcc
	s_add_i32 s2, 0, 0x12000
	v_add_u32_e32 v50, s2, v47
	ds_write_b32 v50, v49 offset:4
	s_or_b64 exec, exec, s[26:27]
	global_load_dword v49, v[2:3], off offset:512
	ds_read_b32 v50, v48 offset:2048
	s_waitcnt vmcnt(0) lgkmcnt(0)
	v_mul_f32_e32 v52, v50, v49
	v_mul_f32_e32 v49, v52, v52
	s_nop 1
	v_mov_b32_dpp v49, v49 quad_perm:[1,0,3,2] row_mask:0xf bank_mask:0xf bound_ctrl:1
	v_fmac_f32_e32 v49, v52, v52
	s_nop 1
	v_add_f32_dpp v49, v49, v49 quad_perm:[2,3,0,1] row_mask:0xf bank_mask:0xf bound_ctrl:1
	s_nop 1
	v_add_f32_dpp v49, v49, v49 row_half_mirror row_mask:0xf bank_mask:0xf bound_ctrl:1
	s_nop 1
	v_add_f32_dpp v49, v49, v49 row_ror:8 row_mask:0xf bank_mask:0xf bound_ctrl:1
	s_nop 0
	v_readlane_b32 s2, v49, 16
	v_readlane_b32 s3, v49, 48
	v_readlane_b32 s26, v49, 0
	v_readlane_b32 s27, v49, 32
	v_mov_b32_e32 v50, s2
	v_mov_b32_e32 v51, s3
	v_pk_add_f32 v[50:51], s[26:27], v[50:51]
	s_nop 0
	v_add_f32_e32 v49, v50, v51
	v_rsq_f32_e32 v49, v49
	s_nop 0
	v_min_f32_e32 v49, 0x5368d4a5, v49
	v_mul_f32_e32 v50, v52, v49
	global_store_dword v[24:25], v50, off offset:512
	s_and_saveexec_b64 s[26:27], vcc
	s_add_i32 s2, 0, 0x12000
	v_add_u32_e32 v50, s2, v47
	ds_write_b32 v50, v49 offset:8
	s_or_b64 exec, exec, s[26:27]
	global_load_dword v49, v[2:3], off offset:768
	ds_read_b32 v48, v48 offset:2304
	s_waitcnt vmcnt(0) lgkmcnt(0)
	v_mul_f32_e32 v50, v48, v49
	v_mul_f32_e32 v48, v50, v50
	s_nop 1
	v_mov_b32_dpp v48, v48 quad_perm:[1,0,3,2] row_mask:0xf bank_mask:0xf bound_ctrl:1
	v_fmac_f32_e32 v48, v50, v50
	s_nop 1
	v_add_f32_dpp v48, v48, v48 quad_perm:[2,3,0,1] row_mask:0xf bank_mask:0xf bound_ctrl:1
	s_nop 1
	v_add_f32_dpp v48, v48, v48 row_half_mirror row_mask:0xf bank_mask:0xf bound_ctrl:1
	s_nop 1
	v_add_f32_dpp v48, v48, v48 row_ror:8 row_mask:0xf bank_mask:0xf bound_ctrl:1
	s_nop 0
	v_readlane_b32 s2, v48, 16
	v_readlane_b32 s3, v48, 48
	v_readlane_b32 s26, v48, 0
	v_readlane_b32 s27, v48, 32
	v_mov_b32_e32 v48, s2
	v_mov_b32_e32 v49, s3
	v_pk_add_f32 v[48:49], s[26:27], v[48:49]
	s_nop 0
	v_add_f32_e32 v48, v48, v49
	v_rsq_f32_e32 v48, v48
	s_nop 0
	v_min_f32_e32 v48, 0x5368d4a5, v48
	v_mul_f32_e32 v49, v50, v48
	global_store_dword v[24:25], v49, off offset:768
	s_and_saveexec_b64 s[26:27], vcc
	s_add_i32 s2, 0, 0x12000
	v_add_u32_e32 v24, s2, v47
	ds_write_b32 v24, v48 offset:12
	s_or_b64 exec, exec, s[26:27]
	v_or_b32_e32 v46, 1, v46
	s_movk_i32 s2, 0x1200
	v_mul_lo_u32 v24, v46, s2
	v_ashrrev_i32_e32 v47, 31, v46
	v_add3_u32 v24, 0, v24, v0
	v_lshl_add_u64 v[48:49], s[34:35], 0, v[46:47]
	v_lshlrev_b32_e32 v0, 4, v46
	global_load_dword v46, v[2:3], off
	ds_read_b32 v25, v24 offset:1536
	v_lshlrev_b64 v[48:49], 10, v[48:49]
	v_lshl_add_u64 v[4:5], v[4:5], 0, v[48:49]
	s_waitcnt vmcnt(0) lgkmcnt(0)
	v_mul_f32_e32 v48, v25, v46
	v_mul_f32_e32 v25, v48, v48
	s_nop 1
	v_mov_b32_dpp v25, v25 quad_perm:[1,0,3,2] row_mask:0xf bank_mask:0xf bound_ctrl:1
	v_fmac_f32_e32 v25, v48, v48
	s_nop 1
	v_add_f32_dpp v25, v25, v25 quad_perm:[2,3,0,1] row_mask:0xf bank_mask:0xf bound_ctrl:1
	s_nop 1
	v_add_f32_dpp v25, v25, v25 row_half_mirror row_mask:0xf bank_mask:0xf bound_ctrl:1
	s_nop 1
	v_add_f32_dpp v25, v25, v25 row_ror:8 row_mask:0xf bank_mask:0xf bound_ctrl:1
	s_nop 0
	v_readlane_b32 s2, v25, 16
	v_readlane_b32 s3, v25, 48
	v_readlane_b32 s26, v25, 0
	v_readlane_b32 s27, v25, 32
	v_mov_b32_e32 v46, s2
	v_mov_b32_e32 v47, s3
	v_pk_add_f32 v[46:47], s[26:27], v[46:47]
	s_nop 0
	v_add_f32_e32 v25, v46, v47
	v_rsq_f32_e32 v25, v25
	s_nop 0
	v_min_f32_e32 v25, 0x5368d4a5, v25
	v_mul_f32_e32 v46, v48, v25
	global_store_dword v[4:5], v46, off
	s_and_saveexec_b64 s[26:27], vcc
	v_add_u32_e32 v46, 0, v0
	v_add_u32_e32 v46, 0x12000, v46
	ds_write_b32 v46, v25
	s_or_b64 exec, exec, s[26:27]
	global_load_dword v25, v[2:3], off offset:256
	ds_read_b32 v46, v24 offset:1792
	s_waitcnt vmcnt(0) lgkmcnt(0)
	v_mul_f32_e32 v48, v46, v25
	v_mul_f32_e32 v25, v48, v48
	s_nop 1
	v_mov_b32_dpp v25, v25 quad_perm:[1,0,3,2] row_mask:0xf bank_mask:0xf bound_ctrl:1
	v_fmac_f32_e32 v25, v48, v48
	s_nop 1
	v_add_f32_dpp v25, v25, v25 quad_perm:[2,3,0,1] row_mask:0xf bank_mask:0xf bound_ctrl:1
	s_nop 1
	v_add_f32_dpp v25, v25, v25 row_half_mirror row_mask:0xf bank_mask:0xf bound_ctrl:1
	s_nop 1
	v_add_f32_dpp v25, v25, v25 row_ror:8 row_mask:0xf bank_mask:0xf bound_ctrl:1
	s_nop 0
	v_readlane_b32 s2, v25, 16
	v_readlane_b32 s3, v25, 48
	v_readlane_b32 s26, v25, 0
	v_readlane_b32 s27, v25, 32
	v_mov_b32_e32 v46, s2
	v_mov_b32_e32 v47, s3
	v_pk_add_f32 v[46:47], s[26:27], v[46:47]
	s_nop 0
	v_add_f32_e32 v25, v46, v47
	v_rsq_f32_e32 v25, v25
	s_nop 0
	v_min_f32_e32 v25, 0x5368d4a5, v25
	v_mul_f32_e32 v46, v48, v25
	global_store_dword v[4:5], v46, off offset:256
	s_and_saveexec_b64 s[26:27], vcc
	s_add_i32 s2, 0, 0x12000
	v_add_u32_e32 v46, s2, v0
	ds_write_b32 v46, v25 offset:4
	s_or_b64 exec, exec, s[26:27]
	global_load_dword v25, v[2:3], off offset:512
	ds_read_b32 v46, v24 offset:2048
	s_waitcnt vmcnt(0) lgkmcnt(0)
	v_mul_f32_e32 v48, v46, v25
	v_mul_f32_e32 v25, v48, v48
	s_nop 1
	v_mov_b32_dpp v25, v25 quad_perm:[1,0,3,2] row_mask:0xf bank_mask:0xf bound_ctrl:1
	v_fmac_f32_e32 v25, v48, v48
	s_nop 1
	v_add_f32_dpp v25, v25, v25 quad_perm:[2,3,0,1] row_mask:0xf bank_mask:0xf bound_ctrl:1
	s_nop 1
	v_add_f32_dpp v25, v25, v25 row_half_mirror row_mask:0xf bank_mask:0xf bound_ctrl:1
	s_nop 1
	v_add_f32_dpp v25, v25, v25 row_ror:8 row_mask:0xf bank_mask:0xf bound_ctrl:1
	s_nop 0
	v_readlane_b32 s2, v25, 16
	v_readlane_b32 s3, v25, 48
	v_readlane_b32 s26, v25, 0
	v_readlane_b32 s27, v25, 32
	v_mov_b32_e32 v46, s2
	v_mov_b32_e32 v47, s3
	v_pk_add_f32 v[46:47], s[26:27], v[46:47]
	s_nop 0
	v_add_f32_e32 v25, v46, v47
	v_rsq_f32_e32 v25, v25
	s_nop 0
	v_min_f32_e32 v25, 0x5368d4a5, v25
	v_mul_f32_e32 v46, v48, v25
	global_store_dword v[4:5], v46, off offset:512
	s_and_saveexec_b64 s[26:27], vcc
	s_add_i32 s2, 0, 0x12000
	v_add_u32_e32 v46, s2, v0
	ds_write_b32 v46, v25 offset:8
	s_or_b64 exec, exec, s[26:27]
	global_load_dword v2, v[2:3], off offset:768
	ds_read_b32 v3, v24 offset:2304
	s_waitcnt vmcnt(0) lgkmcnt(0)
	v_mul_f32_e32 v24, v3, v2
	v_mul_f32_e32 v2, v24, v24
	s_nop 1
	v_mov_b32_dpp v2, v2 quad_perm:[1,0,3,2] row_mask:0xf bank_mask:0xf bound_ctrl:1
	v_fmac_f32_e32 v2, v24, v24
	s_nop 1
	v_add_f32_dpp v2, v2, v2 quad_perm:[2,3,0,1] row_mask:0xf bank_mask:0xf bound_ctrl:1
	s_nop 1
	v_add_f32_dpp v2, v2, v2 row_half_mirror row_mask:0xf bank_mask:0xf bound_ctrl:1
	s_nop 1
	v_add_f32_dpp v2, v2, v2 row_ror:8 row_mask:0xf bank_mask:0xf bound_ctrl:1
	s_nop 0
	v_readlane_b32 s2, v2, 16
	v_readlane_b32 s3, v2, 48
	v_readlane_b32 s26, v2, 0
	v_readlane_b32 s27, v2, 32
	v_mov_b32_e32 v2, s2
	v_mov_b32_e32 v3, s3
	v_pk_add_f32 v[2:3], s[26:27], v[2:3]
	s_nop 0
	v_add_f32_e32 v2, v2, v3
	v_rsq_f32_e32 v2, v2
	s_nop 0
	v_min_f32_e32 v2, 0x5368d4a5, v2
	v_mul_f32_e32 v3, v24, v2
	global_store_dword v[4:5], v3, off offset:768
	s_and_saveexec_b64 s[26:27], vcc
	s_add_i32 s2, 0, 0x12000
	v_add_u32_e32 v0, s2, v0
	ds_write_b32 v0, v2 offset:12
	s_or_b64 exec, exec, s[26:27]
	s_cmp_lt_i32 s44, 0
	s_waitcnt lgkmcnt(0)
	s_barrier
	s_cbranch_scc1 .LBB0_935
	v_readlane_b32 s2, v252, 18
	v_readlane_b32 s3, v252, 19
	s_mov_b64 s[76:77], s[40:41]
	s_lshl_b32 s72, s44, 4
	s_mul_i32 s26, s72, 0x900
	s_add_u32 s42, s2, s26
	s_addc_u32 s43, s3, 0
	s_sub_u32 s46, s42, 0x24000
	s_subb_u32 s47, s43, 0
	s_movk_i32 s49, 0x900
	s_cmpk_lt_i32 s44, 0x400
	s_cbranch_scc0 .Lpi_ctx
	s_and_b32 s48, s72, 0xfff
	v_cmp_gt_u32_e32 vcc, 96, v27
	v_lshlrev_b32_e32 v0, 1, v27
	v_subrev_u32_e32 v2, 96, v27
	v_cndmask_b32_e32 v0, v2, v0, vcc
	v_mul_u32_u24_e32 v0, 0x556, v0
	v_lshrrev_b32_e32 v0, 16, v0
	v_and_b32_e32 v2, 1, v0
	v_lshl_add_u32 v2, v2, 1, -1
	v_lshrrev_b32_e32 v0, 1, v0
	v_mul_u32_u24_e32 v0, 6, v0
	v_lshlrev_b32_e32 v2, v0, v2
	v_lshlrev_b32_e64 v3, v0, 64
	v_add_u32_e32 v3, -1, v3
	v_mul_u32_u24_e32 v4, 0x480, v29
	v_add_lshl_u32 v4, v4, v6, 1
	global_load_dwordx2 v[58:59], v4, s[42:43]
	v_add_u32_e32 v5, 64, v2
	v_mad_u32_u24 v4, v5, s49, v4
	v_add_u32_e32 v5, s48, v29
	v_and_b32_e32 v5, v5, v3
	v_add_u32_e32 v5, v5, v2
	v_cmp_le_u32_e32 vcc, v5, v3
	v_mov_b32_e32 v60, 0
	v_mov_b32_e32 v61, 0
	s_and_saveexec_b64 s[26:27], vcc
	global_load_dwordx2 v[60:61], v4, s[46:47]
	s_mov_b64 exec, s[26:27]
	v_cmp_gt_u32_e32 vcc, 96, v28
	v_lshlrev_b32_e32 v0, 1, v28
	v_subrev_u32_e32 v2, 96, v28
	v_cndmask_b32_e32 v0, v2, v0, vcc
	v_mul_u32_u24_e32 v0, 0x556, v0
	v_lshrrev_b32_e32 v0, 16, v0
	v_and_b32_e32 v2, 1, v0
	v_lshl_add_u32 v2, v2, 1, -1
	v_lshrrev_b32_e32 v0, 1, v0
	v_mul_u32_u24_e32 v0, 6, v0
	v_lshlrev_b32_e32 v2, v0, v2
	v_lshlrev_b32_e64 v3, v0, 64
	v_add_u32_e32 v3, -1, v3
	v_mul_u32_u24_e32 v4, 0x480, v31
	v_add_lshl_u32 v4, v4, v8, 1
	global_load_dwordx2 v[62:63], v4, s[42:43]
	v_add_u32_e32 v5, 64, v2
	v_mad_u32_u24 v4, v5, s49, v4
	v_add_u32_e32 v5, s48, v31
	v_and_b32_e32 v5, v5, v3
	v_add_u32_e32 v5, v5, v2
	v_cmp_le_u32_e32 vcc, v5, v3
	v_mov_b32_e32 v64, 0
	v_mov_b32_e32 v65, 0
	s_and_saveexec_b64 s[26:27], vcc
	global_load_dwordx2 v[64:65], v4, s[46:47]
	s_mov_b64 exec, s[26:27]
	v_cmp_gt_u32_e32 vcc, 96, v30
	v_lshlrev_b32_e32 v0, 1, v30
	v_subrev_u32_e32 v2, 96, v30
	v_cndmask_b32_e32 v0, v2, v0, vcc
	v_mul_u32_u24_e32 v0, 0x556, v0
	v_lshrrev_b32_e32 v0, 16, v0
	v_and_b32_e32 v2, 1, v0
	v_lshl_add_u32 v2, v2, 1, -1
	v_lshrrev_b32_e32 v0, 1, v0
	v_mul_u32_u24_e32 v0, 6, v0
	v_lshlrev_b32_e32 v2, v0, v2
	v_lshlrev_b32_e64 v3, v0, 64
	v_add_u32_e32 v3, -1, v3
	v_mul_u32_u24_e32 v4, 0x480, v33
	v_add_lshl_u32 v4, v4, v10, 1
	global_load_dwordx2 v[66:67], v4, s[42:43]
	v_add_u32_e32 v5, 64, v2
	v_mad_u32_u24 v4, v5, s49, v4
	v_add_u32_e32 v5, s48, v33
	v_and_b32_e32 v5, v5, v3
	v_add_u32_e32 v5, v5, v2
	v_cmp_le_u32_e32 vcc, v5, v3
	v_mov_b32_e32 v68, 0
	v_mov_b32_e32 v69, 0
	s_and_saveexec_b64 s[26:27], vcc
	global_load_dwordx2 v[68:69], v4, s[46:47]
	s_mov_b64 exec, s[26:27]
	v_cmp_gt_u32_e32 vcc, 96, v32
	v_lshlrev_b32_e32 v0, 1, v32
	v_subrev_u32_e32 v2, 96, v32
	v_cndmask_b32_e32 v0, v2, v0, vcc
	v_mul_u32_u24_e32 v0, 0x556, v0
	v_lshrrev_b32_e32 v0, 16, v0
	v_and_b32_e32 v2, 1, v0
	v_lshl_add_u32 v2, v2, 1, -1
	v_lshrrev_b32_e32 v0, 1, v0
	v_mul_u32_u24_e32 v0, 6, v0
	v_lshlrev_b32_e32 v2, v0, v2
	v_lshlrev_b32_e64 v3, v0, 64
	v_add_u32_e32 v3, -1, v3
	v_mul_u32_u24_e32 v4, 0x480, v35
	v_add_lshl_u32 v4, v4, v12, 1
	global_load_dwordx2 v[70:71], v4, s[42:43]
	v_add_u32_e32 v5, 64, v2
	v_mad_u32_u24 v4, v5, s49, v4
	v_add_u32_e32 v5, s48, v35
	v_and_b32_e32 v5, v5, v3
	v_add_u32_e32 v5, v5, v2
	v_cmp_le_u32_e32 vcc, v5, v3
	v_mov_b32_e32 v72, 0
	v_mov_b32_e32 v73, 0
	s_and_saveexec_b64 s[26:27], vcc
	global_load_dwordx2 v[72:73], v4, s[46:47]
	s_mov_b64 exec, s[26:27]
	v_cmp_gt_u32_e32 vcc, 96, v34
	v_lshlrev_b32_e32 v0, 1, v34
	v_subrev_u32_e32 v2, 96, v34
	v_cndmask_b32_e32 v0, v2, v0, vcc
	v_mul_u32_u24_e32 v0, 0x556, v0
	v_lshrrev_b32_e32 v0, 16, v0
	v_and_b32_e32 v2, 1, v0
	v_lshl_add_u32 v2, v2, 1, -1
	v_lshrrev_b32_e32 v0, 1, v0
	v_mul_u32_u24_e32 v0, 6, v0
	v_lshlrev_b32_e32 v2, v0, v2
	v_lshlrev_b32_e64 v3, v0, 64
	v_add_u32_e32 v3, -1, v3
	v_mul_u32_u24_e32 v4, 0x480, v37
	v_add_lshl_u32 v4, v4, v14, 1
	global_load_dwordx2 v[74:75], v4, s[42:43]
	v_add_u32_e32 v5, 64, v2
	v_mad_u32_u24 v4, v5, s49, v4
	v_add_u32_e32 v5, s48, v37
	v_and_b32_e32 v5, v5, v3
	v_add_u32_e32 v5, v5, v2
	v_cmp_le_u32_e32 vcc, v5, v3
	v_mov_b32_e32 v76, 0
	v_mov_b32_e32 v77, 0
	s_and_saveexec_b64 s[26:27], vcc
	global_load_dwordx2 v[76:77], v4, s[46:47]
	s_mov_b64 exec, s[26:27]
	v_cmp_gt_u32_e32 vcc, 96, v36
	v_lshlrev_b32_e32 v0, 1, v36
	v_subrev_u32_e32 v2, 96, v36
	v_cndmask_b32_e32 v0, v2, v0, vcc
	v_mul_u32_u24_e32 v0, 0x556, v0
	v_lshrrev_b32_e32 v0, 16, v0
	v_and_b32_e32 v2, 1, v0
	v_lshl_add_u32 v2, v2, 1, -1
	v_lshrrev_b32_e32 v0, 1, v0
	v_mul_u32_u24_e32 v0, 6, v0
	v_lshlrev_b32_e32 v2, v0, v2
	v_lshlrev_b32_e64 v3, v0, 64
	v_add_u32_e32 v3, -1, v3
	v_mul_u32_u24_e32 v4, 0x480, v39
	v_add_lshl_u32 v4, v4, v16, 1
	global_load_dwordx2 v[78:79], v4, s[42:43]
	v_add_u32_e32 v5, 64, v2
	v_mad_u32_u24 v4, v5, s49, v4
	v_add_u32_e32 v5, s48, v39
	v_and_b32_e32 v5, v5, v3
	v_add_u32_e32 v5, v5, v2
	v_cmp_le_u32_e32 vcc, v5, v3
	v_mov_b32_e32 v80, 0
	v_mov_b32_e32 v81, 0
	s_and_saveexec_b64 s[26:27], vcc
	global_load_dwordx2 v[80:81], v4, s[46:47]
	s_mov_b64 exec, s[26:27]
	v_cmp_gt_u32_e32 vcc, 96, v38
	v_lshlrev_b32_e32 v0, 1, v38
	v_subrev_u32_e32 v2, 96, v38
	v_cndmask_b32_e32 v0, v2, v0, vcc
	v_mul_u32_u24_e32 v0, 0x556, v0
	v_lshrrev_b32_e32 v0, 16, v0
	v_and_b32_e32 v2, 1, v0
	v_lshl_add_u32 v2, v2, 1, -1
	v_lshrrev_b32_e32 v0, 1, v0
	v_mul_u32_u24_e32 v0, 6, v0
	v_lshlrev_b32_e32 v2, v0, v2
	v_lshlrev_b32_e64 v3, v0, 64
	v_add_u32_e32 v3, -1, v3
	v_mul_u32_u24_e32 v4, 0x480, v41
	v_add_lshl_u32 v4, v4, v18, 1
	global_load_dwordx2 v[82:83], v4, s[42:43]
	v_add_u32_e32 v5, 64, v2
	v_mad_u32_u24 v4, v5, s49, v4
	v_add_u32_e32 v5, s48, v41
	v_and_b32_e32 v5, v5, v3
	v_add_u32_e32 v5, v5, v2
	v_cmp_le_u32_e32 vcc, v5, v3
	v_mov_b32_e32 v84, 0
	v_mov_b32_e32 v85, 0
	s_and_saveexec_b64 s[26:27], vcc
	global_load_dwordx2 v[84:85], v4, s[46:47]
	s_mov_b64 exec, s[26:27]
	v_cmp_gt_u32_e32 vcc, 96, v40
	v_lshlrev_b32_e32 v0, 1, v40
	v_subrev_u32_e32 v2, 96, v40
	v_cndmask_b32_e32 v0, v2, v0, vcc
	v_mul_u32_u24_e32 v0, 0x556, v0
	v_lshrrev_b32_e32 v0, 16, v0
	v_and_b32_e32 v2, 1, v0
	v_lshl_add_u32 v2, v2, 1, -1
	v_lshrrev_b32_e32 v0, 1, v0
	v_mul_u32_u24_e32 v0, 6, v0
	v_lshlrev_b32_e32 v2, v0, v2
	v_lshlrev_b32_e64 v3, v0, 64
	v_add_u32_e32 v3, -1, v3
	v_mul_u32_u24_e32 v4, 0x480, v43
	v_add_lshl_u32 v4, v4, v20, 1
	global_load_dwordx2 v[86:87], v4, s[42:43]
	v_add_u32_e32 v5, 64, v2
	v_mad_u32_u24 v4, v5, s49, v4
	v_add_u32_e32 v5, s48, v43
	v_and_b32_e32 v5, v5, v3
	v_add_u32_e32 v5, v5, v2
	v_cmp_le_u32_e32 vcc, v5, v3
	v_mov_b32_e32 v88, 0
	v_mov_b32_e32 v89, 0
	s_and_saveexec_b64 s[26:27], vcc
	global_load_dwordx2 v[88:89], v4, s[46:47]
	s_mov_b64 exec, s[26:27]
	v_cmp_gt_u32_e32 vcc, 96, v42
	v_lshlrev_b32_e32 v0, 1, v42
	v_subrev_u32_e32 v2, 96, v42
	v_cndmask_b32_e32 v0, v2, v0, vcc
	v_mul_u32_u24_e32 v0, 0x556, v0
	v_lshrrev_b32_e32 v0, 16, v0
	v_and_b32_e32 v2, 1, v0
	v_lshl_add_u32 v2, v2, 1, -1
	v_lshrrev_b32_e32 v0, 1, v0
	v_mul_u32_u24_e32 v0, 6, v0
	v_lshlrev_b32_e32 v2, v0, v2
	v_lshlrev_b32_e64 v3, v0, 64
	v_add_u32_e32 v3, -1, v3
	v_mul_u32_u24_e32 v4, 0x480, v45
	v_add_lshl_u32 v4, v4, v22, 1
	global_load_dwordx2 v[90:91], v4, s[42:43]
	v_add_u32_e32 v5, 64, v2
	v_mad_u32_u24 v4, v5, s49, v4
	v_add_u32_e32 v5, s48, v45
	v_and_b32_e32 v5, v5, v3
	v_add_u32_e32 v5, v5, v2
	v_cmp_le_u32_e32 vcc, v5, v3
	v_mov_b32_e32 v92, 0
	v_mov_b32_e32 v93, 0
	s_and_saveexec_b64 s[26:27], vcc
	global_load_dwordx2 v[92:93], v4, s[46:47]
	s_mov_b64 exec, s[26:27]
	s_branch .Lpi_done
.Lpi_ctx:
	s_and_b32 s48, s72, 0xff
	v_cmp_gt_u32_e32 vcc, 96, v27
	v_lshlrev_b32_e32 v0, 1, v27
	v_subrev_u32_e32 v2, 96, v27
	v_cndmask_b32_e32 v0, v2, v0, vcc
	v_cmp_lt_u32_e32 vcc, 0x5f, v0
	v_cndmask_b32_e64 v2, -1, 1, vcc
	v_mul_u32_u24_e32 v4, 0x480, v29
	v_add_lshl_u32 v4, v4, v6, 1
	global_load_dwordx2 v[58:59], v4, s[42:43]
	v_add_u32_e32 v5, 64, v2
	v_mad_u32_u24 v4, v5, s49, v4
	v_add_u32_e32 v5, s48, v29
	v_add_u32_e32 v5, v5, v2
	v_cmp_gt_u32_e32 vcc, 0x100, v5
	v_mov_b32_e32 v60, 0
	v_mov_b32_e32 v61, 0
	s_and_saveexec_b64 s[26:27], vcc
	global_load_dwordx2 v[60:61], v4, s[46:47]
	s_mov_b64 exec, s[26:27]
	v_cmp_gt_u32_e32 vcc, 96, v28
	v_lshlrev_b32_e32 v0, 1, v28
	v_subrev_u32_e32 v2, 96, v28
	v_cndmask_b32_e32 v0, v2, v0, vcc
	v_cmp_lt_u32_e32 vcc, 0x5f, v0
	v_cndmask_b32_e64 v2, -1, 1, vcc
	v_mul_u32_u24_e32 v4, 0x480, v31
	v_add_lshl_u32 v4, v4, v8, 1
	global_load_dwordx2 v[62:63], v4, s[42:43]
	v_add_u32_e32 v5, 64, v2
	v_mad_u32_u24 v4, v5, s49, v4
	v_add_u32_e32 v5, s48, v31
	v_add_u32_e32 v5, v5, v2
	v_cmp_gt_u32_e32 vcc, 0x100, v5
	v_mov_b32_e32 v64, 0
	v_mov_b32_e32 v65, 0
	s_and_saveexec_b64 s[26:27], vcc
	global_load_dwordx2 v[64:65], v4, s[46:47]
	s_mov_b64 exec, s[26:27]
	v_cmp_gt_u32_e32 vcc, 96, v30
	v_lshlrev_b32_e32 v0, 1, v30
	v_subrev_u32_e32 v2, 96, v30
	v_cndmask_b32_e32 v0, v2, v0, vcc
	v_cmp_lt_u32_e32 vcc, 0x5f, v0
	v_cndmask_b32_e64 v2, -1, 1, vcc
	v_mul_u32_u24_e32 v4, 0x480, v33
	v_add_lshl_u32 v4, v4, v10, 1
	global_load_dwordx2 v[66:67], v4, s[42:43]
	v_add_u32_e32 v5, 64, v2
	v_mad_u32_u24 v4, v5, s49, v4
	v_add_u32_e32 v5, s48, v33
	v_add_u32_e32 v5, v5, v2
	v_cmp_gt_u32_e32 vcc, 0x100, v5
	v_mov_b32_e32 v68, 0
	v_mov_b32_e32 v69, 0
	s_and_saveexec_b64 s[26:27], vcc
	global_load_dwordx2 v[68:69], v4, s[46:47]
	s_mov_b64 exec, s[26:27]
	v_cmp_gt_u32_e32 vcc, 96, v32
	v_lshlrev_b32_e32 v0, 1, v32
	v_subrev_u32_e32 v2, 96, v32
	v_cndmask_b32_e32 v0, v2, v0, vcc
	v_cmp_lt_u32_e32 vcc, 0x5f, v0
	v_cndmask_b32_e64 v2, -1, 1, vcc
	v_mul_u32_u24_e32 v4, 0x480, v35
	v_add_lshl_u32 v4, v4, v12, 1
	global_load_dwordx2 v[70:71], v4, s[42:43]
	v_add_u32_e32 v5, 64, v2
	v_mad_u32_u24 v4, v5, s49, v4
	v_add_u32_e32 v5, s48, v35
	v_add_u32_e32 v5, v5, v2
	v_cmp_gt_u32_e32 vcc, 0x100, v5
	v_mov_b32_e32 v72, 0
	v_mov_b32_e32 v73, 0
	s_and_saveexec_b64 s[26:27], vcc
	global_load_dwordx2 v[72:73], v4, s[46:47]
	s_mov_b64 exec, s[26:27]
	v_cmp_gt_u32_e32 vcc, 96, v34
	v_lshlrev_b32_e32 v0, 1, v34
	v_subrev_u32_e32 v2, 96, v34
	v_cndmask_b32_e32 v0, v2, v0, vcc
	v_cmp_lt_u32_e32 vcc, 0x5f, v0
	v_cndmask_b32_e64 v2, -1, 1, vcc
	v_mul_u32_u24_e32 v4, 0x480, v37
	v_add_lshl_u32 v4, v4, v14, 1
	global_load_dwordx2 v[74:75], v4, s[42:43]
	v_add_u32_e32 v5, 64, v2
	v_mad_u32_u24 v4, v5, s49, v4
	v_add_u32_e32 v5, s48, v37
	v_add_u32_e32 v5, v5, v2
	v_cmp_gt_u32_e32 vcc, 0x100, v5
	v_mov_b32_e32 v76, 0
	v_mov_b32_e32 v77, 0
	s_and_saveexec_b64 s[26:27], vcc
	global_load_dwordx2 v[76:77], v4, s[46:47]
	s_mov_b64 exec, s[26:27]
	v_cmp_gt_u32_e32 vcc, 96, v36
	v_lshlrev_b32_e32 v0, 1, v36
	v_subrev_u32_e32 v2, 96, v36
	v_cndmask_b32_e32 v0, v2, v0, vcc
	v_cmp_lt_u32_e32 vcc, 0x5f, v0
	v_cndmask_b32_e64 v2, -1, 1, vcc
	v_mul_u32_u24_e32 v4, 0x480, v39
	v_add_lshl_u32 v4, v4, v16, 1
	global_load_dwordx2 v[78:79], v4, s[42:43]
	v_add_u32_e32 v5, 64, v2
	v_mad_u32_u24 v4, v5, s49, v4
	v_add_u32_e32 v5, s48, v39
	v_add_u32_e32 v5, v5, v2
	v_cmp_gt_u32_e32 vcc, 0x100, v5
	v_mov_b32_e32 v80, 0
	v_mov_b32_e32 v81, 0
	s_and_saveexec_b64 s[26:27], vcc
	global_load_dwordx2 v[80:81], v4, s[46:47]
	s_mov_b64 exec, s[26:27]
	v_cmp_gt_u32_e32 vcc, 96, v38
	v_lshlrev_b32_e32 v0, 1, v38
	v_subrev_u32_e32 v2, 96, v38
	v_cndmask_b32_e32 v0, v2, v0, vcc
	v_cmp_lt_u32_e32 vcc, 0x5f, v0
	v_cndmask_b32_e64 v2, -1, 1, vcc
	v_mul_u32_u24_e32 v4, 0x480, v41
	v_add_lshl_u32 v4, v4, v18, 1
	global_load_dwordx2 v[82:83], v4, s[42:43]
	v_add_u32_e32 v5, 64, v2
	v_mad_u32_u24 v4, v5, s49, v4
	v_add_u32_e32 v5, s48, v41
	v_add_u32_e32 v5, v5, v2
	v_cmp_gt_u32_e32 vcc, 0x100, v5
	v_mov_b32_e32 v84, 0
	v_mov_b32_e32 v85, 0
	s_and_saveexec_b64 s[26:27], vcc
	global_load_dwordx2 v[84:85], v4, s[46:47]
	s_mov_b64 exec, s[26:27]
	v_cmp_gt_u32_e32 vcc, 96, v40
	v_lshlrev_b32_e32 v0, 1, v40
	v_subrev_u32_e32 v2, 96, v40
	v_cndmask_b32_e32 v0, v2, v0, vcc
	v_cmp_lt_u32_e32 vcc, 0x5f, v0
	v_cndmask_b32_e64 v2, -1, 1, vcc
	v_mul_u32_u24_e32 v4, 0x480, v43
	v_add_lshl_u32 v4, v4, v20, 1
	global_load_dwordx2 v[86:87], v4, s[42:43]
	v_add_u32_e32 v5, 64, v2
	v_mad_u32_u24 v4, v5, s49, v4
	v_add_u32_e32 v5, s48, v43
	v_add_u32_e32 v5, v5, v2
	v_cmp_gt_u32_e32 vcc, 0x100, v5
	v_mov_b32_e32 v88, 0
	v_mov_b32_e32 v89, 0
	s_and_saveexec_b64 s[26:27], vcc
	global_load_dwordx2 v[88:89], v4, s[46:47]
	s_mov_b64 exec, s[26:27]
	v_cmp_gt_u32_e32 vcc, 96, v42
	v_lshlrev_b32_e32 v0, 1, v42
	v_subrev_u32_e32 v2, 96, v42
	v_cndmask_b32_e32 v0, v2, v0, vcc
	v_cmp_lt_u32_e32 vcc, 0x5f, v0
	v_cndmask_b32_e64 v2, -1, 1, vcc
	v_mul_u32_u24_e32 v4, 0x480, v45
	v_add_lshl_u32 v4, v4, v22, 1
	global_load_dwordx2 v[90:91], v4, s[42:43]
	v_add_u32_e32 v5, 64, v2
	v_mad_u32_u24 v4, v5, s49, v4
	v_add_u32_e32 v5, s48, v45
	v_add_u32_e32 v5, v5, v2
	v_cmp_gt_u32_e32 vcc, 0x100, v5
	v_mov_b32_e32 v92, 0
	v_mov_b32_e32 v93, 0
	s_and_saveexec_b64 s[26:27], vcc
	global_load_dwordx2 v[92:93], v4, s[46:47]
	s_mov_b64 exec, s[26:27]
.Lpi_done:
.LBB0_935:
	v_and_b32_e32 v0, 15, v26
	v_ashrrev_i32_e32 v3, 7, v26
	s_movk_i32 s2, 0x1200
	v_or_b32_e32 v50, s34, v0
	v_mad_u32_u24 v108, v0, s2, 0
	v_lshlrev_b32_e32 v0, 4, v0
	s_add_i32 s2, 0, 0x12000
	v_lshlrev_b32_e32 v3, 2, v3
	v_add3_u32 v4, s2, v0, v3
	v_readlane_b32 s2, v250, 58
	v_lshlrev_b32_e32 v0, 4, v44
	v_readlane_b32 s3, v250, 59
	v_lshrrev_b32_e32 v2, 4, v44
	v_mov_b32_e32 v51, s35
	v_lshl_add_u64 v[96:97], s[2:3], 0, v[0:1]
	v_readlane_b32 s2, v252, 12
	v_lshlrev_b32_e32 v95, 2, v2
	v_lshl_add_u32 v0, v2, 5, v108
	v_lshlrev_b64 v[2:3], 9, v[50:51]
	v_readlane_b32 s3, v252, 13
	s_mov_b32 s26, 0
	s_mov_b64 s[34:35], -1
	v_lshl_add_u64 v[98:99], s[2:3], 0, v[2:3]
	ds_read_b32 v100, v4
	ds_read_b128 v[2:5], v0 offset:1024
	ds_read_b128 v[6:9], v0 offset:1040
	v_readlane_b32 s2, v252, 0
	v_readlane_b32 s3, v252, 1
	s_waitcnt lgkmcnt(2)
	v_mov_b32_e32 v101, v100
	s_waitcnt lgkmcnt(1)
	v_cvt_pk_bf16_f32 v2, v2, v3
	v_cvt_pk_bf16_f32 v3, v4, v5
	s_waitcnt lgkmcnt(0)
	v_cvt_pk_bf16_f32 v4, v6, v7
	v_cvt_pk_bf16_f32 v5, v8, v9
	ds_read_b128 v[6:9], v0 offset:1152
	ds_read_b128 v[10:13], v0 offset:1168
	s_waitcnt lgkmcnt(1)
	v_cvt_pk_bf16_f32 v6, v6, v7
	v_cvt_pk_bf16_f32 v7, v8, v9
	s_waitcnt lgkmcnt(0)
	v_cvt_pk_bf16_f32 v8, v10, v11
	v_cvt_pk_bf16_f32 v9, v12, v13
	ds_read_b128 v[10:13], v0 offset:1280
	ds_read_b128 v[14:17], v0 offset:1296
	s_waitcnt lgkmcnt(1)
	v_cvt_pk_bf16_f32 v10, v10, v11
	v_cvt_pk_bf16_f32 v11, v12, v13
	s_waitcnt lgkmcnt(0)
	v_cvt_pk_bf16_f32 v12, v14, v15
	v_cvt_pk_bf16_f32 v13, v16, v17
	ds_read_b128 v[14:17], v0 offset:1408
	ds_read_b128 v[18:21], v0 offset:1424
	s_waitcnt lgkmcnt(1)
	v_cvt_pk_bf16_f32 v14, v14, v15
	v_cvt_pk_bf16_f32 v15, v16, v17
	s_waitcnt lgkmcnt(0)
	v_cvt_pk_bf16_f32 v16, v18, v19
	v_cvt_pk_bf16_f32 v17, v20, v21
	ds_read_b128 v[18:21], v0 offset:3584
	ds_read_b128 v[22:25], v0 offset:3600
	s_waitcnt lgkmcnt(1)
	v_cvt_pk_bf16_f32 v18, v18, v19
	v_cvt_pk_bf16_f32 v19, v20, v21
	s_waitcnt lgkmcnt(0)
	v_cvt_pk_bf16_f32 v20, v22, v23
	v_cvt_pk_bf16_f32 v21, v24, v25
	ds_read_b128 v[22:25], v0 offset:4096
	ds_read_b128 v[26:29], v0 offset:4112
	s_waitcnt lgkmcnt(1)
	v_cvt_pk_bf16_f32 v22, v22, v23
	v_cvt_pk_bf16_f32 v23, v24, v25
	s_waitcnt lgkmcnt(0)
	v_cvt_pk_bf16_f32 v24, v26, v27
	v_cvt_pk_bf16_f32 v25, v28, v29
	ds_read_b128 v[26:29], v0 offset:3712
	ds_read_b128 v[30:33], v0 offset:3728
	s_waitcnt lgkmcnt(1)
	v_cvt_pk_bf16_f32 v26, v26, v27
	v_cvt_pk_bf16_f32 v27, v28, v29
	s_waitcnt lgkmcnt(0)
	v_cvt_pk_bf16_f32 v28, v30, v31
	v_cvt_pk_bf16_f32 v29, v32, v33
	ds_read_b128 v[30:33], v0 offset:4224
	ds_read_b128 v[34:37], v0 offset:4240
	s_waitcnt lgkmcnt(1)
	v_cvt_pk_bf16_f32 v30, v30, v31
	v_cvt_pk_bf16_f32 v31, v32, v33
	s_waitcnt lgkmcnt(0)
	v_cvt_pk_bf16_f32 v32, v34, v35
	v_cvt_pk_bf16_f32 v33, v36, v37
	ds_read_b128 v[34:37], v0 offset:3840
	ds_read_b128 v[38:41], v0 offset:3856
	s_waitcnt lgkmcnt(1)
	v_cvt_pk_bf16_f32 v34, v34, v35
	v_cvt_pk_bf16_f32 v35, v36, v37
	s_waitcnt lgkmcnt(0)
	v_cvt_pk_bf16_f32 v36, v38, v39
	v_cvt_pk_bf16_f32 v37, v40, v41
	ds_read_b128 v[38:41], v0 offset:4352
	ds_read_b128 v[42:45], v0 offset:4368
	s_waitcnt lgkmcnt(1)
	v_cvt_pk_bf16_f32 v38, v38, v39
	v_cvt_pk_bf16_f32 v39, v40, v41
	s_waitcnt lgkmcnt(0)
	v_cvt_pk_bf16_f32 v40, v42, v43
	v_cvt_pk_bf16_f32 v41, v44, v45
	ds_read_b128 v[42:45], v0 offset:3968
	ds_read_b128 v[46:49], v0 offset:3984
	s_waitcnt lgkmcnt(1)
	v_cvt_pk_bf16_f32 v42, v42, v43
	v_cvt_pk_bf16_f32 v43, v44, v45
	s_waitcnt lgkmcnt(0)
	v_cvt_pk_bf16_f32 v44, v46, v47
	v_cvt_pk_bf16_f32 v45, v48, v49
	ds_read_b128 v[46:49], v0 offset:4480
	ds_read_b128 v[52:55], v0 offset:4496
	s_waitcnt lgkmcnt(1)
	v_cvt_pk_bf16_f32 v46, v46, v47
	v_cvt_pk_bf16_f32 v47, v48, v49
	s_waitcnt lgkmcnt(0)
	v_cvt_pk_bf16_f32 v48, v52, v53
	v_lshlrev_b64 v[52:53], 11, v[50:51]
	v_lshl_add_u64 v[102:103], s[2:3], 0, v[52:53]
	v_readlane_b32 s2, v252, 22
	v_readlane_b32 s3, v252, 23
	v_lshlrev_b64 v[50:51], 10, v[50:51]
	v_cvt_pk_bf16_f32 v49, v54, v55
	v_lshl_add_u64 v[104:105], s[2:3], 0, v[52:53]
	v_readlane_b32 s2, v252, 6
	v_readlane_b32 s3, v252, 7
	s_nop 1
	v_lshl_add_u64 v[106:107], s[2:3], 0, v[50:51]
	s_mov_b32 s2, 0x18000
	s_mov_b32 s3, 0x20000
.LBB0_936:
	v_or_b32_e32 v0, s26, v94
	v_lshlrev_b32_e32 v114, 2, v0
	v_lshl_or_b32 v146, v0, 4, v95
	v_ashrrev_i32_e32 v115, 31, v114
	v_ashrrev_i32_e32 v147, 31, v146
	v_lshlrev_b64 v[114:115], 10, v[114:115]
	v_lshlrev_b64 v[188:189], 2, v[146:147]
	v_lshl_add_u64 v[114:115], v[96:97], 0, v[114:115]
	v_lshl_add_u64 v[54:55], s[86:87], 0, v[188:189]
	v_add_co_u32_e32 v126, vcc, s3, v114
	v_lshl_add_u32 v50, v146, 2, v108
	global_load_dwordx4 v[110:113], v[54:55], off
	v_lshl_add_u64 v[54:55], s[84:85], 0, v[188:189]
	v_addc_co_u32_e32 v127, vcc, 0, v115, vcc
	ds_read_b128 v[50:53], v50 offset:1536
	global_load_dwordx4 v[54:57], v[54:55], off
	s_nop 0
	global_load_dwordx4 v[114:117], v[126:127], off
	global_load_dwordx4 v[118:121], v[126:127], off offset:1024
	global_load_dwordx4 v[122:125], v[126:127], off offset:2048
	s_nop 0
	global_load_dwordx4 v[126:129], v[126:127], off offset:3072
	v_lshlrev_b32_e32 v172, 1, v0
	v_ashrrev_i32_e32 v173, 31, v172
	v_lshlrev_b64 v[130:131], 10, v[172:173]
	v_lshl_add_u64 v[168:169], v[96:97], 0, v[130:131]
	global_load_dwordx4 v[130:133], v[168:169], off
	v_or_b32_e32 v138, 1, v172
	v_ashrrev_i32_e32 v139, 31, v138
	v_add_co_u32_e32 v142, vcc, s20, v168
	v_lshlrev_b64 v[138:139], 10, v[138:139]
	s_nop 0
	v_addc_co_u32_e32 v143, vcc, 0, v169, vcc
	v_lshl_add_u64 v[138:139], v[96:97], 0, v[138:139]
	global_load_dwordx4 v[134:137], v[142:143], off
	s_nop 0
	global_load_dwordx4 v[138:141], v[138:139], off
	s_nop 0
	global_load_dwordx4 v[142:145], v[142:143], off offset:1024
	v_lshl_add_u64 v[180:181], s[88:89], 0, v[188:189]
	global_load_dwordx4 v[156:159], v[180:181], off
	v_lshl_add_u64 v[184:185], s[0:1], 0, v[188:189]
	global_load_dwordx4 v[160:163], v[184:185], off
	v_add_co_u32_e32 v164, vcc, s22, v168
	v_add_u32_e32 v172, 33, v172
	s_nop 0
	v_addc_co_u32_e32 v165, vcc, 0, v169, vcc
	v_ashrrev_i32_e32 v173, 31, v172
	v_add_co_u32_e32 v176, vcc, s2, v168
	v_lshlrev_b64 v[172:173], 10, v[172:173]
	s_nop 0
	v_addc_co_u32_e32 v177, vcc, 0, v169, vcc
	v_lshl_add_u64 v[172:173], v[96:97], 0, v[172:173]
	global_load_dwordx4 v[164:167], v[164:165], off
	s_mov_b32 s26, 1
	global_load_dwordx4 v[168:171], v[176:177], off
	s_nop 0
	global_load_dwordx4 v[172:175], v[172:173], off
	s_nop 0
	global_load_dwordx4 v[176:179], v[176:177], off offset:1024
	s_nop 0
	global_load_dwordx4 v[180:183], v[180:181], off offset:1024
	s_nop 0
	global_load_dwordx4 v[184:187], v[184:185], off offset:1024
	s_and_b64 vcc, exec, s[34:35]
	s_mov_b64 s[34:35], 0
	s_waitcnt vmcnt(15)
	v_mfma_f32_16x16x32_bf16 v[114:117], v[114:117], v[2:5], 0
	s_waitcnt lgkmcnt(0)
	v_pk_mul_f32 v[110:111], v[50:51], v[110:111]
	v_pk_mul_f32 v[112:113], v[52:53], v[112:113]
	s_waitcnt vmcnt(14)
	v_mfma_f32_16x16x32_bf16 v[114:117], v[118:121], v[6:9], v[114:117]
	s_waitcnt vmcnt(13)
	v_mfma_f32_16x16x32_bf16 v[114:117], v[122:125], v[10:13], v[114:117]
	v_lshlrev_b64 v[122:123], 1, v[146:147]
	v_pk_mul_f32 v[124:125], v[110:111], v[100:101]
	s_waitcnt vmcnt(12)
	v_mfma_f32_16x16x32_bf16 v[114:117], v[126:129], v[14:17], v[114:117]
	v_mul_f32_e64 v128, v112, v100
	v_mul_f32_e64 v129, v113, v101
	s_waitcnt vmcnt(10)
	v_mfma_f32_16x16x32_bf16 v[118:121], v[134:137], v[22:25], 0
	s_nop 3
	v_cvt_pk_bf16_f32 v114, v114, v115
	v_cvt_pk_bf16_f32 v115, v116, v117
	v_lshl_add_u64 v[116:117], v[98:99], 0, v[122:123]
	global_store_dwordx2 v[116:117], v[114:115], off
	v_mfma_f32_16x16x32_bf16 v[114:117], v[130:133], v[18:21], 0
	v_lshl_add_u64 v[130:131], v[104:105], 0, v[188:189]
	s_waitcnt vmcnt(10)
	v_mfma_f32_16x16x32_bf16 v[114:117], v[138:141], v[26:29], v[114:117]
	s_waitcnt vmcnt(9)
	v_mfma_f32_16x16x32_bf16 v[118:121], v[142:145], v[30:33], v[118:121]
	s_waitcnt vmcnt(8)
	s_nop 4
	v_add_f32_e32 v0, v156, v114
	v_mul_f32_e32 v0, 0xbfb8aa3b, v0
	v_exp_f32_e32 v0, v0
	s_nop 0
	v_add_f32_e32 v0, 1.0, v0
	v_rcp_f32_e32 v0, v0
	s_nop 0
	v_mul_f32_e32 v0, 0xbf1b4598, v0
	v_mul_f32_e32 v0, 0x3fb8aa3b, v0
	v_exp_f32_e32 v114, v0
	s_waitcnt vmcnt(7)
	v_add_f32_e32 v0, v160, v118
	v_mul_f32_e32 v0, 0xbfb8aa3b, v0
	v_exp_f32_e32 v0, v0
	s_nop 0
	v_add_f32_e32 v0, 1.0, v0
	v_rcp_f32_e32 v118, v0
	v_add_f32_e32 v0, v157, v115
	v_mul_f32_e32 v0, 0xbfb8aa3b, v0
	v_exp_f32_e32 v0, v0
	s_nop 0
	v_add_f32_e32 v0, 1.0, v0
	v_rcp_f32_e32 v0, v0
	s_nop 0
	v_mul_f32_e32 v0, 0xbf1b4598, v0
	v_mul_f32_e32 v0, 0x3fb8aa3b, v0
	v_exp_f32_e32 v115, v0
	v_add_f32_e32 v0, v161, v119
	v_mul_f32_e32 v0, 0xbfb8aa3b, v0
	v_exp_f32_e32 v0, v0
	s_nop 0
	v_add_f32_e32 v0, 1.0, v0
	v_rcp_f32_e32 v119, v0
	v_add_f32_e32 v0, v158, v116
	v_mul_f32_e32 v0, 0xbfb8aa3b, v0
	v_exp_f32_e32 v0, v0
	v_pk_add_f32 v[110:111], v[118:119], -1.0 op_sel_hi:[1,0]
	v_add_f32_e32 v0, 1.0, v0
	v_rcp_f32_e32 v0, v0
	v_pk_fma_f32 v[110:111], v[54:55], v[110:111], 1.0 op_sel_hi:[1,1,0]
	v_mul_f32_e32 v0, 0xbf1b4598, v0
	v_mul_f32_e32 v0, 0x3fb8aa3b, v0
	v_exp_f32_e32 v116, v0
	v_add_f32_e32 v0, v162, v120
	v_mul_f32_e32 v0, 0xbfb8aa3b, v0
	v_exp_f32_e32 v0, v0
	v_pk_mul_f32 v[126:127], v[50:51], v[110:111]
	v_pk_mul_f32 v[110:111], v[124:125], v[118:119]
	v_add_f32_e32 v0, 1.0, v0
	v_rcp_f32_e32 v120, v0
	v_add_f32_e32 v0, v159, v117
	v_mul_f32_e32 v0, 0xbfb8aa3b, v0
	v_exp_f32_e32 v0, v0
	s_nop 0
	v_add_f32_e32 v0, 1.0, v0
	v_rcp_f32_e32 v0, v0
	s_nop 0
	v_mul_f32_e32 v0, 0xbf1b4598, v0
	v_mul_f32_e32 v0, 0x3fb8aa3b, v0
	v_exp_f32_e32 v117, v0
	v_add_f32_e32 v0, v163, v121
	v_mul_f32_e32 v0, 0xbfb8aa3b, v0
	v_exp_f32_e32 v0, v0
	s_nop 0
	v_add_f32_e32 v0, 1.0, v0
	v_rcp_f32_e32 v121, v0
	s_nop 0
	v_pk_add_f32 v[118:119], v[120:121], -1.0 op_sel_hi:[1,0]
	s_nop 0
	v_pk_fma_f32 v[118:119], v[56:57], v[118:119], 1.0 op_sel_hi:[1,1,0]
	v_pk_mul_f32 v[112:113], v[128:129], v[120:121]
	v_pk_mul_f32 v[118:119], v[52:53], v[118:119]
	v_lshl_add_u64 v[120:121], v[102:103], 0, v[188:189]
	global_store_dwordx4 v[130:131], v[110:113], off
	global_store_dwordx4 v[120:121], v[114:117], off
	s_nop 0
	v_cvt_pk_bf16_f32 v110, v126, v127
	v_cvt_pk_bf16_f32 v111, v118, v119
	v_lshl_add_u64 v[118:119], v[106:107], 0, v[122:123]
	global_store_dwordx2 v[118:119], v[110:111], off
	s_waitcnt vmcnt(9)
	v_mfma_f32_16x16x32_bf16 v[110:113], v[164:167], v[34:37], 0
	s_waitcnt vmcnt(7)
	v_mfma_f32_16x16x32_bf16 v[110:113], v[172:175], v[42:45], v[110:113]
	v_mfma_f32_16x16x32_bf16 v[114:117], v[168:171], v[38:41], 0
	s_waitcnt vmcnt(6)
	v_mfma_f32_16x16x32_bf16 v[114:117], v[176:179], v[46:49], v[114:117]
	s_waitcnt vmcnt(5)
	s_nop 3
	v_add_f32_e32 v0, v180, v110
	v_mul_f32_e32 v0, 0xbfb8aa3b, v0
	v_exp_f32_e32 v0, v0
	s_nop 0
	v_add_f32_e32 v0, 1.0, v0
	v_rcp_f32_e32 v0, v0
	s_nop 0
	v_mul_f32_e32 v0, 0xbf1b4598, v0
	v_mul_f32_e32 v0, 0x3fb8aa3b, v0
	v_exp_f32_e32 v110, v0
	s_waitcnt vmcnt(4)
	v_add_f32_e32 v0, v184, v114
	v_mul_f32_e32 v0, 0xbfb8aa3b, v0
	v_exp_f32_e32 v0, v0
	s_nop 0
	v_add_f32_e32 v0, 1.0, v0
	v_rcp_f32_e32 v114, v0
	v_add_f32_e32 v0, v181, v111
	v_mul_f32_e32 v0, 0xbfb8aa3b, v0
	v_exp_f32_e32 v0, v0
	s_nop 0
	v_add_f32_e32 v0, 1.0, v0
	v_rcp_f32_e32 v0, v0
	s_nop 0
	v_mul_f32_e32 v0, 0xbf1b4598, v0
	v_mul_f32_e32 v0, 0x3fb8aa3b, v0
	v_exp_f32_e32 v111, v0
	v_add_f32_e32 v0, v185, v115
	v_mul_f32_e32 v0, 0xbfb8aa3b, v0
	v_exp_f32_e32 v0, v0
	s_nop 0
	v_add_f32_e32 v0, 1.0, v0
	v_rcp_f32_e32 v115, v0
	v_add_f32_e32 v0, v182, v112
	v_mul_f32_e32 v0, 0xbfb8aa3b, v0
	v_exp_f32_e32 v0, v0
	v_pk_add_f32 v[122:123], v[114:115], -1.0 op_sel_hi:[1,0]
	v_pk_mul_f32 v[114:115], v[124:125], v[114:115]
	v_pk_fma_f32 v[54:55], v[54:55], v[122:123], 1.0 op_sel_hi:[1,1,0]
	v_add_f32_e32 v0, 1.0, v0
	v_rcp_f32_e32 v0, v0
	v_pk_mul_f32 v[50:51], v[50:51], v[54:55]
	v_mul_f32_e32 v0, 0xbf1b4598, v0
	v_mul_f32_e32 v0, 0x3fb8aa3b, v0
	v_exp_f32_e32 v112, v0
	v_add_f32_e32 v0, v186, v116
	v_mul_f32_e32 v0, 0xbfb8aa3b, v0
	v_exp_f32_e32 v0, v0
	v_cvt_pk_bf16_f32 v50, v50, v51
	v_add_f32_e32 v0, 1.0, v0
	v_rcp_f32_e32 v54, v0
	v_add_f32_e32 v0, v183, v113
	v_mul_f32_e32 v0, 0xbfb8aa3b, v0
	v_exp_f32_e32 v0, v0
	s_nop 0
	v_add_f32_e32 v0, 1.0, v0
	v_rcp_f32_e32 v0, v0
	s_nop 0
	v_mul_f32_e32 v0, 0xbf1b4598, v0
	v_mul_f32_e32 v0, 0x3fb8aa3b, v0
	v_exp_f32_e32 v113, v0
	v_add_f32_e32 v0, v187, v117
	v_mul_f32_e32 v0, 0xbfb8aa3b, v0
	v_exp_f32_e32 v0, v0
	s_nop 0
	v_add_f32_e32 v0, 1.0, v0
	v_rcp_f32_e32 v55, v0
	s_nop 0
	v_pk_mul_f32 v[116:117], v[128:129], v[54:55]
	v_pk_add_f32 v[54:55], v[54:55], -1.0 op_sel_hi:[1,0]
	global_store_dwordx4 v[120:121], v[110:113], off offset:1024
	global_store_dwordx4 v[130:131], v[114:117], off offset:1024
	v_pk_fma_f32 v[54:55], v[56:57], v[54:55], 1.0 op_sel_hi:[1,1,0]
	s_nop 0
	v_pk_mul_f32 v[52:53], v[52:53], v[54:55]
	s_nop 0
	v_cvt_pk_bf16_f32 v51, v52, v53
	global_store_dwordx2 v[118:119], v[50:51], off offset:512
	s_cbranch_vccnz .LBB0_936
	s_barrier
	s_waitcnt vmcnt(0)
	v_readlane_b32 s2, v251, 40
	v_readlane_b32 s3, v251, 41
	s_barrier
	s_and_saveexec_b64 s[26:27], s[2:3]
	s_cbranch_execz .LBB0_531
	s_mov_b64 s[34:35], exec
	v_mbcnt_lo_u32_b32 v0, s34, 0
	buffer_wbl2 sc1
	s_waitcnt vmcnt(0)
	s_waitcnt vmcnt(0)
	v_mbcnt_hi_u32_b32 v0, s35, v0
	v_cmp_eq_u32_e32 vcc, 0, v0
	s_and_b64 s[42:43], exec, vcc
	s_mov_b64 exec, s[42:43]
	s_cbranch_execz .LBB0_531
	s_addk_i32 s31, 0xff00
	s_ashr_i32 s2, s31, 31
	v_readlane_b32 s3, v249, 36
	s_xor_b32 s2, s2, s3
	s_abs_i32 s3, s31
	v_readlane_b32 s4, v249, 37
	s_mul_hi_u32 s31, s3, s4
	s_mul_i32 s33, s31, s37
	s_sub_i32 s3, s3, s33
	s_add_i32 s33, s31, 1
	s_sub_i32 s42, s3, s37
	s_cmp_ge_u32 s3, s37
	s_cselect_b32 s31, s33, s31
	s_cselect_b32 s3, s42, s3
	s_add_i32 s33, s31, 1
	s_cmp_ge_u32 s3, s37
	s_cselect_b32 s3, s33, s31
	s_xor_b32 s3, s3, s2
	s_sub_i32 s2, s3, s2
	s_lshl_b32 s42, s2, 6
	s_ashr_i32 s43, s42, 31
	s_lshl_b64 s[42:43], s[42:43], 2
	v_readlane_b32 s2, v250, 56
	s_add_u32 s42, s2, s42
	v_readlane_b32 s2, v250, 57
	s_addc_u32 s43, s2, s43
	s_bcnt1_i32_b64 s2, s[34:35]
	v_mov_b32_e32 v0, s2
	global_atomic_add v1, v0, s[42:43]
	s_branch .LBB0_531
.LBB0_942:
	s_add_i32 s48, s30, 0xffffff80
	v_readlane_b32 s2, v250, 18
	s_cmp_ge_i32 s48, s2
	s_cbranch_scc1 .LBB0_1000
	v_readlane_b32 s2, v249, 27
	s_add_i32 s24, s2, s30
	s_mov_b32 s31, s48
	s_branch .LBB0_946
